# additional start stagger by column-tile parity (block id bit 6): one sleep in SwiGLU GEMM and one more in in-proj GEMM, on top of v56
# baseline (speedup 1.0000x reference)
.LBB0_139:
	s_and_b64 vcc, exec, s[8:9]
	s_cbranch_vccz .LBB0_152
	v_readlane_b32 s98, v255, 18
	s_bitcmp0_b32 s98, 6
	s_cbranch_scc1 .Lstag_skip_sw
	s_sleep 0x7f

.LBB0_971:
	v_readlane_b32 s98, v255, 18
	s_bitcmp0_b32 s98, 6
	s_cbranch_scc1 .Lstag_skip_pj
	s_sleep 0x7f
